# FoX loop: two K/V tiles in flight (second staging register set chosen by tile parity) + hand-scheduled fast path for unmasked tiles
# speedup vs baseline: 1.0421x; 1.0200x over previous
.LBB0_945:
	v_lshlrev_b64 v[116:117], 1, v[68:69]
	v_lshl_add_u64 v[8:9], v[98:99], 0, v[116:117]
	global_load_dwordx4 v[98:101], v[8:9], off
	v_lshlrev_b64 v[8:9], 1, v[72:73]
	v_lshl_add_u64 v[10:11], s[40:41], 0, v[8:9]
	s_lshl_b64 s[0:1], s[6:7], 1
	v_lshl_add_u64 v[10:11], v[10:11], 0, s[0:1]
	v_lshl_add_u64 v[10:11], v[10:11], 0, v[116:117]
	global_load_dwordx4 v[102:105], v[10:11], off
	v_lshl_add_u64 v[10:11], s[38:39], 0, v[74:75]
	v_lshl_add_u64 v[10:11], v[10:11], 0, v[116:117]
	v_lshlrev_b32_e32 v139, 3, v108
	global_load_dwordx4 v[106:109], v[10:11], off
	v_lshlrev_b64 v[10:11], 1, v[76:77]
	v_lshl_add_u64 v[12:13], s[40:41], 0, v[10:11]
	v_lshl_add_u64 v[12:13], v[12:13], 0, s[0:1]
	v_lshl_add_u64 v[12:13], v[12:13], 0, v[116:117]
	global_load_dwordx4 v[110:113], v[12:13], off
	v_fmaak_f32 v4, -2.0, v67, 0xc3160000
	v_cndmask_b32_e64 v140, v212, v4, s[4:5]
	v_sub_f32_e32 v34, v2, v5
	v_lshl_add_u64 v[4:5], s[40:41], 0, v[6:7]
	v_lshl_add_u64 v[4:5], v[4:5], 0, s[22:23]
	v_mov_b32_e32 v16, v1
	v_mov_b32_e32 v17, v1
	v_lshl_add_u64 v[120:121], v[4:5], 0, v[10:11]
	v_lshl_add_u64 v[122:123], v[4:5], 0, v[8:9]
	v_add_u32_e32 v142, 0xffffff00, v3
	v_mov_b32_e32 v2, v1
	v_mov_b32_e32 v3, v1
	v_mov_b32_e32 v4, v1
	v_mov_b32_e32 v5, v1
	v_mov_b32_e32 v6, v1
	v_mov_b32_e32 v7, v1
	v_mov_b32_e32 v8, v1
	v_mov_b32_e32 v9, v1
	v_mov_b32_e32 v10, v1
	v_mov_b32_e32 v11, v1
	v_mov_b32_e32 v12, v1
	v_mov_b32_e32 v13, v1
	v_mov_b32_e32 v14, v1
	v_mov_b32_e32 v15, v1
	v_mov_b64_e32 v[32:33], v[16:17]
	v_mul_u32_u24_e32 v141, 0x88, v118
	v_mov_b32_e32 v35, v34
	v_mov_b32_e32 v36, v34
	v_mov_b32_e32 v37, v34
	v_mov_b32_e32 v38, v34
	v_mov_b32_e32 v39, v34
	v_mov_b32_e32 v40, v34
	v_mov_b32_e32 v41, v34
	v_mov_b32_e32 v42, v34
	v_mov_b32_e32 v43, v34
	v_mov_b32_e32 v44, v34
	v_lshl_add_u64 v[118:119], s[38:39], 0, v[78:79]
	v_lshl_add_u64 v[124:125], s[38:39], 0, v[80:81]
	s_mov_b32 s6, 0
	v_mov_b32_e32 v138, 0
	v_mov_b32_e32 v45, v34
	v_mov_b32_e32 v46, v34
	v_mov_b32_e32 v47, v34
	v_mov_b32_e32 v48, v34
	v_mov_b32_e32 v49, v34
	v_mov_b64_e32 v[30:31], v[14:15]
	v_mov_b64_e32 v[28:29], v[12:13]
	v_mov_b64_e32 v[26:27], v[10:11]
	v_mov_b64_e32 v[24:25], v[8:9]
	v_mov_b64_e32 v[22:23], v[6:7]
	v_mov_b64_e32 v[20:21], v[4:5]
	v_mov_b64_e32 v[18:19], v[2:3]
	v_lshl_add_u64 v[52:53], v[118:119], 0, v[116:117]
	global_load_dwordx4 v[218:221], v[52:53], off
	v_lshl_add_u64 v[52:53], v[122:123], 0, v[116:117]
	global_load_dwordx4 v[222:225], v[52:53], off
	v_lshl_add_u64 v[52:53], v[124:125], 0, v[116:117]
	global_load_dwordx4 v[226:229], v[52:53], off
	v_lshl_add_u64 v[52:53], v[120:121], 0, v[116:117]
	global_load_dwordx4 v[230:233], v[52:53], off
	v_lshl_add_u64 v[118:119], v[118:119], 0, s[18:19]
	v_lshl_add_u64 v[124:125], v[124:125], 0, s[18:19]
	v_lshl_add_u64 v[120:121], v[120:121], 0, s[26:27]
	v_lshl_add_u64 v[122:123], v[122:123], 0, s[26:27]
.LBB0_946:
	s_mul_i32 s37, s6, 0x4800
	ds_read_b32 v217, v142 offset:252
	s_cmpk_le_u32 s44, 0x80
	s_cbranch_scc1 .Lfox_top_tail
	s_cmp_eq_u32 s6, 0
	s_cbranch_scc0 .Lfox_top_b
	v_add3_u32 v50, s37, v132, v133
	v_lshl_add_u64 v[52:53], v[118:119], 0, v[116:117]
	s_waitcnt vmcnt(7)
	ds_write_b128 v50, v[98:101] offset:32768
	global_load_dwordx4 v[98:101], v[52:53], off
	v_add_u32_e32 v50, s37, v134
	v_add3_u32 v50, v50, v133, s95
	v_lshl_add_u64 v[52:53], v[122:123], 0, v[116:117]
	s_waitcnt vmcnt(7)
	ds_write2_b64 v50, v[102:103], v[104:105] offset1:1
	global_load_dwordx4 v[102:105], v[52:53], off
	v_add3_u32 v50, s37, v130, v133
	v_lshl_add_u64 v[52:53], v[124:125], 0, v[116:117]
	s_waitcnt vmcnt(7)
	ds_write_b128 v50, v[106:109] offset:32768
	global_load_dwordx4 v[106:109], v[52:53], off
	v_add_u32_e32 v50, s37, v131
	v_add3_u32 v50, v50, v133, s95
	v_lshl_add_u64 v[52:53], v[120:121], 0, v[116:117]
	s_waitcnt vmcnt(7)
	ds_write2_b64 v50, v[110:111], v[112:113] offset1:1
	global_load_dwordx4 v[110:113], v[52:53], off
	s_branch .LBB0_948
.Lfox_top_b:
	v_add3_u32 v50, s37, v132, v133
	v_lshl_add_u64 v[52:53], v[118:119], 0, v[116:117]
	s_waitcnt vmcnt(7)
	ds_write_b128 v50, v[218:221] offset:32768
	global_load_dwordx4 v[218:221], v[52:53], off
	v_add_u32_e32 v50, s37, v134
	v_add3_u32 v50, v50, v133, s95
	v_lshl_add_u64 v[52:53], v[122:123], 0, v[116:117]
	s_waitcnt vmcnt(7)
	ds_write2_b64 v50, v[222:223], v[224:225] offset1:1
	global_load_dwordx4 v[222:225], v[52:53], off
	v_add3_u32 v50, s37, v130, v133
	v_lshl_add_u64 v[52:53], v[124:125], 0, v[116:117]
	s_waitcnt vmcnt(7)
	ds_write_b128 v50, v[226:229] offset:32768
	global_load_dwordx4 v[226:229], v[52:53], off
	v_add_u32_e32 v50, s37, v131
	v_add3_u32 v50, v50, v133, s95
	v_lshl_add_u64 v[52:53], v[120:121], 0, v[116:117]
	s_waitcnt vmcnt(7)
	ds_write2_b64 v50, v[230:231], v[232:233] offset1:1
	global_load_dwordx4 v[230:233], v[52:53], off
	s_branch .LBB0_948
.Lfox_top_tail:
	s_cmp_eq_u32 s44, 64
	s_cbranch_scc1 .Lfox_tail_w0
	s_waitcnt vmcnt(4)
	s_branch .Lfox_tail_wr

.Lfox_tail_wr:
	s_cmp_eq_u32 s6, 0
	s_cbranch_scc0 .Lfox_tail_b
	v_add3_u32 v50, s37, v132, v133
	ds_write_b128 v50, v[98:101] offset:32768
	v_add_u32_e32 v50, s37, v134
	v_add3_u32 v50, v50, v133, s95
	ds_write2_b64 v50, v[102:103], v[104:105] offset1:1
	v_add3_u32 v50, s37, v130, v133
	ds_write_b128 v50, v[106:109] offset:32768
	v_add_u32_e32 v50, s37, v131
	v_add3_u32 v50, v50, v133, s95
	ds_write2_b64 v50, v[110:111], v[112:113] offset1:1
	s_branch .LBB0_948
.Lfox_tail_b:
	v_add3_u32 v50, s37, v132, v133
	ds_write_b128 v50, v[218:221] offset:32768
	v_add_u32_e32 v50, s37, v134
	v_add3_u32 v50, v50, v133, s95
	ds_write2_b64 v50, v[222:223], v[224:225] offset1:1
	v_add3_u32 v50, s37, v130, v133
	ds_write_b128 v50, v[226:229] offset:32768
	v_add_u32_e32 v50, s37, v131
	v_add3_u32 v50, v50, v133, s95
	ds_write2_b64 v50, v[230:231], v[232:233] offset1:1
.LBB0_948:
	s_add_i32 s4, s44, -1
	s_cmp_ge_i32 s4, s63
	s_cselect_b64 s[0:1], -1, 0
	s_and_b64 vcc, exec, s[0:1]
	s_waitcnt lgkmcnt(0)
	s_barrier
	s_cbranch_vccnz .LBB0_950
	v_sub_f32_e32 v50, v127, v217
	v_cmp_nlt_f32_e64 s[0:1], v50, v140
.LBB0_950:
	s_andn2_b64 vcc, exec, s[0:1]
	s_cbranch_vccnz .LBB0_956
	s_sub_i32 s36, s44, 64
	v_cmp_le_i32_e32 vcc, s36, v129
	s_cmp_eq_u64 vcc, exec
	s_cbranch_scc0 .Lfox_old
	v_cmp_gt_i32_e64 s[100:101], s4, v128
	s_cmp_eq_u64 s[100:101], 0
	s_cbranch_scc0 .Lfox_old
	s_mov_b64 s[0:1], exec
	v_add_u32_e32 v181, v142, v136
	ds_read_b128 v[234:237], v181
	ds_read_b128 v[238:241], v181 offset:32
	ds_read_b128 v[242:245], v181 offset:64
	ds_read_b128 v[246:249], v181 offset:96
	v_add3_u32 v152, s37, v136, v135
	ds_read_b128 v[144:147], v152 offset:32768
	ds_read_b128 v[148:151], v152 offset:32800
	v_add3_u32 v180, s37, v141, v139
	v_add_u32_e32 v180, 0xa400, v180
	s_waitcnt lgkmcnt(2)
	v_sub_f32_e32 v66, v34, v234
	v_sub_f32_e32 v67, v35, v235
	v_sub_f32_e32 v68, v36, v236
	v_sub_f32_e32 v69, v37, v237
	v_sub_f32_e32 v70, v38, v238
	v_sub_f32_e32 v71, v39, v239
	v_sub_f32_e32 v72, v40, v240
	v_sub_f32_e32 v73, v41, v241
	v_sub_f32_e32 v74, v42, v242
	v_sub_f32_e32 v75, v43, v243
	v_sub_f32_e32 v76, v44, v244
	v_sub_f32_e32 v77, v45, v245
	v_sub_f32_e32 v78, v46, v246
	v_sub_f32_e32 v79, v47, v247
	v_sub_f32_e32 v80, v48, v248
	v_sub_f32_e32 v81, v49, v249
	ds_read_b128 v[234:237], v181 offset:128
	ds_read_b128 v[238:241], v181 offset:160
	ds_read_b128 v[242:245], v181 offset:192
	ds_read_b128 v[246:249], v181 offset:224
	ds_read_b128 v[164:167], v152 offset:32832
	ds_read_b128 v[168:171], v152 offset:32864
	s_waitcnt lgkmcnt(7)
	v_mfma_f32_32x32x16_bf16 v[66:81], v[144:147], v[82:85], v[66:81]
	ds_read_b128 v[144:147], v152 offset:37376
	s_waitcnt lgkmcnt(7)
	v_mfma_f32_32x32x16_bf16 v[66:81], v[148:151], v[86:89], v[66:81]
	ds_read_b128 v[148:151], v152 offset:37408
	s_waitcnt lgkmcnt(4)
	v_sub_f32_e32 v50, v34, v234
	v_sub_f32_e32 v51, v35, v235
	v_sub_f32_e32 v52, v36, v236
	v_sub_f32_e32 v53, v37, v237
	v_sub_f32_e32 v54, v38, v238
	v_sub_f32_e32 v55, v39, v239
	v_sub_f32_e32 v56, v40, v240
	v_sub_f32_e32 v57, v41, v241
	s_waitcnt lgkmcnt(3)
	v_mfma_f32_32x32x16_bf16 v[66:81], v[164:167], v[90:93], v[66:81]
	ds_read_b128 v[164:167], v152 offset:37440
	v_sub_f32_e32 v58, v42, v242
	v_sub_f32_e32 v59, v43, v243
	v_sub_f32_e32 v60, v44, v244
	v_sub_f32_e32 v61, v45, v245
	v_sub_f32_e32 v62, v46, v246
	v_sub_f32_e32 v63, v47, v247
	v_sub_f32_e32 v64, v48, v248
	v_sub_f32_e32 v65, v49, v249
	s_waitcnt lgkmcnt(3)
	v_mfma_f32_32x32x16_bf16 v[66:81], v[168:171], v[94:97], v[66:81]
	ds_read_b128 v[168:171], v152 offset:37472
	s_waitcnt lgkmcnt(3)
	v_mfma_f32_32x32x16_bf16 v[50:65], v[144:147], v[82:85], v[50:65]
	ds_read_b64 v[144:145], v180
	ds_read_b64 v[146:147], v180 offset:16
	s_waitcnt lgkmcnt(4)
	v_mfma_f32_32x32x16_bf16 v[50:65], v[148:151], v[86:89], v[50:65]
	ds_read_b64 v[148:149], v180 offset:4352
	ds_read_b64 v[150:151], v180 offset:4368
	s_waitcnt lgkmcnt(5)
	v_mfma_f32_32x32x16_bf16 v[50:65], v[164:167], v[90:93], v[50:65]
	ds_read_b64 v[164:165], v180 offset:32
	ds_read_b64 v[166:167], v180 offset:48
	v_exp_f32_e32 v66, v66
	v_exp_f32_e32 v67, v67
	v_exp_f32_e32 v68, v68
	v_exp_f32_e32 v69, v69
	s_waitcnt lgkmcnt(6)
	v_mfma_f32_32x32x16_bf16 v[50:65], v[168:171], v[94:97], v[50:65]
	ds_read_b64 v[168:169], v180 offset:4384
	ds_read_b64 v[170:171], v180 offset:4400
	v_exp_f32_e32 v70, v70
	v_exp_f32_e32 v71, v71
	v_exp_f32_e32 v72, v72
	v_exp_f32_e32 v73, v73
	v_cvt_pk_bf16_f32 v172, v66, v67
	v_cvt_pk_bf16_f32 v173, v68, v69
	v_cvt_pk_bf16_f32 v174, v70, v71
	v_cvt_pk_bf16_f32 v175, v72, v73
	s_nop 0
	s_waitcnt lgkmcnt(6)
	v_mfma_f32_32x32x16_bf16 v[18:33], v[144:147], v[172:175], v[18:33]
	ds_read_b64 v[144:145], v180 offset:64
	ds_read_b64 v[146:147], v180 offset:80
	v_exp_f32_e32 v74, v74
	v_exp_f32_e32 v75, v75
	v_exp_f32_e32 v76, v76
	v_exp_f32_e32 v77, v77
	v_exp_f32_e32 v78, v78
	v_exp_f32_e32 v79, v79
	v_exp_f32_e32 v80, v80
	v_exp_f32_e32 v81, v81
	v_cvt_pk_bf16_f32 v176, v74, v75
	v_cvt_pk_bf16_f32 v177, v76, v77
	s_waitcnt lgkmcnt(6)
	v_mfma_f32_32x32x16_bf16 v[2:17], v[148:151], v[172:175], v[2:17]
	ds_read_b64 v[148:149], v180 offset:4416
	ds_read_b64 v[150:151], v180 offset:4432
	v_cvt_pk_bf16_f32 v178, v78, v79
	v_cvt_pk_bf16_f32 v179, v80, v81
	v_add_f32_e32 v66, v66, v67
	v_add_f32_e32 v68, v68, v69
	v_add_f32_e32 v70, v70, v71
	v_add_f32_e32 v72, v72, v73
	v_add_f32_e32 v66, v66, v68
	v_add_f32_e32 v70, v70, v72
	v_add_f32_e32 v66, v66, v70
	v_add_f32_e32 v138, v138, v66
	s_waitcnt lgkmcnt(6)
	v_mfma_f32_32x32x16_bf16 v[18:33], v[164:167], v[176:179], v[18:33]
	ds_read_b64 v[164:165], v180 offset:96
	ds_read_b64 v[166:167], v180 offset:112
	v_exp_f32_e32 v50, v50
	v_exp_f32_e32 v51, v51
	v_exp_f32_e32 v52, v52
	v_exp_f32_e32 v53, v53
	v_exp_f32_e32 v54, v54
	v_exp_f32_e32 v55, v55
	v_exp_f32_e32 v56, v56
	v_exp_f32_e32 v57, v57
	v_cvt_pk_bf16_f32 v172, v50, v51
	v_cvt_pk_bf16_f32 v173, v52, v53
	s_waitcnt lgkmcnt(6)
	v_mfma_f32_32x32x16_bf16 v[2:17], v[168:171], v[176:179], v[2:17]
	ds_read_b64 v[168:169], v180 offset:4448
	ds_read_b64 v[170:171], v180 offset:4464
	v_cvt_pk_bf16_f32 v174, v54, v55
	v_cvt_pk_bf16_f32 v175, v56, v57
	v_add_f32_e32 v74, v74, v75
	v_add_f32_e32 v76, v76, v77
	v_add_f32_e32 v78, v78, v79
	v_add_f32_e32 v80, v80, v81
	v_add_f32_e32 v74, v74, v76
	v_add_f32_e32 v78, v78, v80
	v_add_f32_e32 v74, v74, v78
	v_add_f32_e32 v138, v138, v74
	s_waitcnt lgkmcnt(6)
	v_mfma_f32_32x32x16_bf16 v[18:33], v[144:147], v[172:175], v[18:33]
	v_exp_f32_e32 v58, v58
	v_exp_f32_e32 v59, v59
	v_exp_f32_e32 v60, v60
	v_exp_f32_e32 v61, v61
	v_exp_f32_e32 v62, v62
	v_exp_f32_e32 v63, v63
	v_exp_f32_e32 v64, v64
	v_exp_f32_e32 v65, v65
	v_cvt_pk_bf16_f32 v176, v58, v59
	v_cvt_pk_bf16_f32 v177, v60, v61
	s_waitcnt lgkmcnt(4)
	v_mfma_f32_32x32x16_bf16 v[2:17], v[148:151], v[172:175], v[2:17]
	v_cvt_pk_bf16_f32 v178, v62, v63
	v_cvt_pk_bf16_f32 v179, v64, v65
	v_add_f32_e32 v50, v50, v51
	v_add_f32_e32 v52, v52, v53
	v_add_f32_e32 v54, v54, v55
	v_add_f32_e32 v56, v56, v57
	v_add_f32_e32 v50, v50, v52
	v_add_f32_e32 v54, v54, v56
	v_add_f32_e32 v50, v50, v54
	v_add_f32_e32 v138, v138, v50
	s_waitcnt lgkmcnt(2)
	v_mfma_f32_32x32x16_bf16 v[18:33], v[164:167], v[176:179], v[18:33]
	v_add_f32_e32 v58, v58, v59
	v_add_f32_e32 v60, v60, v61
	v_add_f32_e32 v62, v62, v63
	v_add_f32_e32 v64, v64, v65
	s_waitcnt lgkmcnt(0)
	v_mfma_f32_32x32x16_bf16 v[2:17], v[168:171], v[176:179], v[2:17]
	v_add_f32_e32 v58, v58, v60
	v_add_f32_e32 v62, v62, v64
	v_add_f32_e32 v58, v58, v62
	v_add_f32_e32 v138, v138, v58
	s_branch .LBB0_955
.Lfox_old:
	s_and_saveexec_b64 s[0:1], vcc
	s_cbranch_execz .LBB0_955
	v_add_u32_e32 v143, v142, v136
	ds_read_b128 v[50:53], v143 offset:96
	ds_read_b128 v[54:57], v143 offset:64
	v_add3_u32 v152, s37, v136, v135
	v_cmp_gt_i32_e32 vcc, s4, v128
	s_waitcnt lgkmcnt(1)
	v_sub_f32_e32 v81, v49, v53
	v_sub_f32_e32 v80, v48, v52
	v_sub_f32_e32 v79, v47, v51
	v_sub_f32_e32 v78, v46, v50
	s_waitcnt lgkmcnt(0)
	v_sub_f32_e32 v77, v45, v57
	v_sub_f32_e32 v76, v44, v56
	v_sub_f32_e32 v75, v43, v55
	v_sub_f32_e32 v74, v42, v54
	ds_read_b128 v[50:53], v143 offset:32
	ds_read_b128 v[54:57], v143
	s_waitcnt lgkmcnt(1)
	v_sub_f32_e32 v73, v41, v53
	v_sub_f32_e32 v72, v40, v52
	v_sub_f32_e32 v71, v39, v51
	v_sub_f32_e32 v70, v38, v50
	s_waitcnt lgkmcnt(0)
	v_sub_f32_e32 v69, v37, v57
	v_sub_f32_e32 v68, v36, v56
	v_sub_f32_e32 v67, v35, v55
	v_sub_f32_e32 v66, v34, v54
	ds_read_b128 v[50:53], v152 offset:32768
	ds_read_b128 v[54:57], v152 offset:32800
	s_waitcnt lgkmcnt(1)
	v_mfma_f32_32x32x16_bf16 v[66:81], v[50:53], v[82:85], v[66:81]
	ds_read_b128 v[50:53], v143 offset:224
	ds_read_b128 v[58:61], v143 offset:192
	s_waitcnt lgkmcnt(1)
	v_sub_f32_e32 v65, v49, v53
	v_sub_f32_e32 v64, v48, v52
	v_sub_f32_e32 v63, v47, v51
	v_mfma_f32_32x32x16_bf16 v[66:81], v[54:57], v[86:89], v[66:81]
	v_sub_f32_e32 v62, v46, v50
	ds_read_b128 v[50:53], v152 offset:32832
	ds_read_b128 v[144:147], v152 offset:32864
	s_waitcnt lgkmcnt(2)
	v_sub_f32_e32 v61, v45, v61
	v_sub_f32_e32 v60, v44, v60
	v_sub_f32_e32 v59, v43, v59
	v_sub_f32_e32 v58, v42, v58
	s_waitcnt lgkmcnt(1)
	v_mfma_f32_32x32x16_bf16 v[66:81], v[50:53], v[90:93], v[66:81]
	ds_read_b128 v[50:53], v143 offset:160
	ds_read_b128 v[148:151], v143 offset:128
	s_waitcnt lgkmcnt(1)
	v_sub_f32_e32 v57, v41, v53
	v_sub_f32_e32 v56, v40, v52
	v_sub_f32_e32 v55, v39, v51
	v_sub_f32_e32 v54, v38, v50
	s_waitcnt lgkmcnt(0)
	v_sub_f32_e32 v53, v37, v151
	v_sub_f32_e32 v52, v36, v150
	v_sub_f32_e32 v51, v35, v149
	v_sub_f32_e32 v50, v34, v148
	v_mfma_f32_32x32x16_bf16 v[66:81], v[144:147], v[94:97], v[66:81]
	ds_read_b128 v[144:147], v152 offset:37376
	ds_read_b128 v[148:151], v152 offset:37408
	s_waitcnt lgkmcnt(1)
	v_mfma_f32_32x32x16_bf16 v[50:65], v[144:147], v[82:85], v[50:65]
	s_waitcnt lgkmcnt(0)
	v_mfma_f32_32x32x16_bf16 v[50:65], v[148:151], v[86:89], v[50:65]
	ds_read_b128 v[144:147], v152 offset:37440
	ds_read_b128 v[148:151], v152 offset:37472
	s_waitcnt lgkmcnt(1)
	v_mfma_f32_32x32x16_bf16 v[50:65], v[144:147], v[90:93], v[50:65]
	s_waitcnt lgkmcnt(0)
	v_mfma_f32_32x32x16_bf16 v[50:65], v[148:151], v[94:97], v[50:65]
	s_and_saveexec_b64 s[4:5], vcc
	s_cbranch_execz .LBB0_954
	v_add_u32_e32 v143, s44, v0
	v_subrev_u32_e32 v144, 64, v143
	v_cmp_lt_i32_e32 vcc, v144, v126
	s_nop 1
	v_cndmask_b32_e32 v67, v215, v67, vcc
	v_cmp_le_i32_e32 vcc, v144, v126
	v_subrev_u32_e32 v144, 62, v143
	s_nop 0
	v_cndmask_b32_e32 v66, v215, v66, vcc
	v_cmp_le_i32_e32 vcc, v144, v126
	v_subrev_u32_e32 v144, 61, v143
	s_nop 0
	v_cndmask_b32_e32 v68, v215, v68, vcc
	v_cmp_le_i32_e32 vcc, v144, v126
	v_subrev_u32_e32 v144, 56, v143
	s_nop 0
	v_cndmask_b32_e32 v69, v215, v69, vcc
	v_cmp_le_i32_e32 vcc, v144, v126
	v_subrev_u32_e32 v144, 55, v143
	s_nop 0
	v_cndmask_b32_e32 v70, v215, v70, vcc
	v_cmp_le_i32_e32 vcc, v144, v126
	v_subrev_u32_e32 v144, 54, v143
	s_nop 0
	v_cndmask_b32_e32 v71, v215, v71, vcc
	v_cmp_le_i32_e32 vcc, v144, v126
	v_subrev_u32_e32 v144, 53, v143
	s_nop 0
	v_cndmask_b32_e32 v72, v215, v72, vcc
	v_cmp_le_i32_e32 vcc, v144, v126
	v_subrev_u32_e32 v144, 48, v143
	s_nop 0
	v_cndmask_b32_e32 v73, v215, v73, vcc
	v_cmp_le_i32_e32 vcc, v144, v126
	v_subrev_u32_e32 v144, 47, v143
	s_nop 0
	v_cndmask_b32_e32 v74, v215, v74, vcc
	v_cmp_le_i32_e32 vcc, v144, v126
	v_subrev_u32_e32 v144, 46, v143
	s_nop 0
	v_cndmask_b32_e32 v75, v215, v75, vcc
	v_cmp_le_i32_e32 vcc, v144, v126
	v_subrev_u32_e32 v144, 45, v143
	s_nop 0
	v_cndmask_b32_e32 v76, v215, v76, vcc
	v_cmp_le_i32_e32 vcc, v144, v126
	v_subrev_u32_e32 v144, 40, v143
	s_nop 0
	v_cndmask_b32_e32 v77, v215, v77, vcc
	v_cmp_le_i32_e32 vcc, v144, v126
	v_subrev_u32_e32 v144, 39, v143
	s_nop 0
	v_cndmask_b32_e32 v78, v215, v78, vcc
	v_cmp_le_i32_e32 vcc, v144, v126
	v_subrev_u32_e32 v144, 38, v143
	s_nop 0
	v_cndmask_b32_e32 v79, v215, v79, vcc
	v_cmp_le_i32_e32 vcc, v144, v126
	v_subrev_u32_e32 v144, 37, v143
	s_nop 0
	v_cndmask_b32_e32 v80, v215, v80, vcc
	v_cmp_le_i32_e32 vcc, v144, v126
	v_subrev_u32_e32 v144, 32, v143
	s_nop 0
	v_cndmask_b32_e32 v81, v215, v81, vcc
	v_cmp_le_i32_e32 vcc, v144, v126
	v_subrev_u32_e32 v144, 31, v143
	s_nop 0
	v_cndmask_b32_e32 v50, v215, v50, vcc
	v_cmp_le_i32_e32 vcc, v144, v126
	v_subrev_u32_e32 v144, 30, v143
	s_nop 0
	v_cndmask_b32_e32 v51, v215, v51, vcc
	v_cmp_le_i32_e32 vcc, v144, v126
	v_subrev_u32_e32 v144, 29, v143
	s_nop 0
	v_cndmask_b32_e32 v52, v215, v52, vcc
	v_cmp_le_i32_e32 vcc, v144, v126
	v_subrev_u32_e32 v144, 24, v143
	s_nop 0
	v_cndmask_b32_e32 v53, v215, v53, vcc
	v_cmp_le_i32_e32 vcc, v144, v126
	v_subrev_u32_e32 v144, 23, v143
	s_nop 0
	v_cndmask_b32_e32 v54, v215, v54, vcc
	v_cmp_le_i32_e32 vcc, v144, v126
	v_subrev_u32_e32 v144, 22, v143
	s_nop 0
	v_cndmask_b32_e32 v55, v215, v55, vcc
	v_cmp_le_i32_e32 vcc, v144, v126
	v_subrev_u32_e32 v144, 21, v143
	s_nop 0
	v_cndmask_b32_e32 v56, v215, v56, vcc
	v_cmp_le_i32_e32 vcc, v144, v126
	v_add_u32_e32 v144, -16, v143
	s_nop 0
	v_cndmask_b32_e32 v57, v215, v57, vcc
	v_cmp_le_i32_e32 vcc, v144, v126
	v_add_u32_e32 v144, -15, v143
	s_nop 0
	v_cndmask_b32_e32 v58, v215, v58, vcc
	v_cmp_le_i32_e32 vcc, v144, v126
	v_add_u32_e32 v144, -14, v143
	s_nop 0
	v_cndmask_b32_e32 v59, v215, v59, vcc
	v_cmp_le_i32_e32 vcc, v144, v126
	v_add_u32_e32 v144, -13, v143
	s_nop 0
	v_cndmask_b32_e32 v60, v215, v60, vcc
	v_cmp_le_i32_e32 vcc, v144, v126
	v_add_u32_e32 v144, -8, v143
	s_nop 0
	v_cndmask_b32_e32 v61, v215, v61, vcc
	v_cmp_le_i32_e32 vcc, v144, v126
	v_add_u32_e32 v144, -7, v143
	s_nop 0
	v_cndmask_b32_e32 v62, v215, v62, vcc
	v_cmp_le_i32_e32 vcc, v144, v126
	v_add_u32_e32 v144, -6, v143
	v_add_u32_e32 v143, -5, v143
	v_cndmask_b32_e32 v63, v215, v63, vcc
	v_cmp_le_i32_e32 vcc, v144, v126
	s_nop 1
	v_cndmask_b32_e32 v64, v215, v64, vcc
	v_cmp_le_i32_e32 vcc, v143, v126
	s_nop 1
	v_cndmask_b32_e32 v65, v215, v65, vcc

.LBB0_958:
	s_waitcnt vmcnt(0)
	ds_bpermute_b32 v34, v205, v138
	v_cmp_gt_i32_e32 vcc, s45, v114
	s_and_saveexec_b64 s[0:1], vcc
	s_cbranch_execz .LBB0_828
	s_lshl_b32 s4, s55, s34
	s_add_i32 s6, s4, s62
	v_ashrrev_i32_e32 v115, 31, v115
	v_lshl_add_u64 v[36:37], v[114:115], 0, s[6:7]
	s_lshl_b32 s4, s54, 6
	v_lshlrev_b64 v[36:37], 11, v[36:37]
	s_ashr_i32 s5, s4, 31
	v_lshl_add_u64 v[38:39], s[10:11], 0, v[36:37]
	s_lshl_b64 s[4:5], s[4:5], 1
	v_lshl_add_u64 v[38:39], v[38:39], 0, s[4:5]
	v_lshlrev_b64 v[40:41], 1, v[0:1]
	v_lshl_add_u64 v[38:39], v[38:39], 0, v[40:41]
	global_load_dwordx2 v[42:43], v[38:39], off
	global_load_dwordx2 v[44:45], v[38:39], off offset:16
	global_load_dwordx2 v[46:47], v[38:39], off offset:32
	global_load_dwordx2 v[48:49], v[38:39], off offset:48
	global_load_dwordx2 v[50:51], v[38:39], off offset:64
	global_load_dwordx2 v[52:53], v[38:39], off offset:80
	s_waitcnt lgkmcnt(0)
	v_add_f32_e32 v0, v138, v34
	global_load_dwordx2 v[34:35], v[38:39], off offset:96
	v_div_scale_f32 v54, s[30:31], v0, v0, 1.0
	global_load_dwordx2 v[38:39], v[38:39], off offset:112
	v_rcp_f32_e32 v56, v54
	v_lshl_add_u64 v[36:37], s[12:13], 0, v[36:37]
	v_div_scale_f32 v55, vcc, 1.0, v0, 1.0
	v_fma_f32 v57, -v54, v56, 1.0
	v_lshl_add_u64 v[36:37], v[36:37], 0, s[4:5]
	v_fmac_f32_e32 v56, v57, v56
	v_lshl_add_u64 v[36:37], v[36:37], 0, v[40:41]
	v_mul_f32_e32 v40, v55, v56
	v_fma_f32 v41, -v54, v40, v55
	v_fmac_f32_e32 v40, v41, v56
	v_fma_f32 v41, -v54, v40, v55
	v_div_fmas_f32 v40, v41, v56, v40
	v_div_fixup_f32 v0, v40, v0, 1.0
	v_pk_mul_f32 v[18:19], v[18:19], v[0:1] op_sel_hi:[1,0]
	v_pk_mul_f32 v[20:21], v[20:21], v[0:1] op_sel_hi:[1,0]
	v_pk_mul_f32 v[2:3], v[2:3], v[0:1] op_sel_hi:[1,0]
	v_pk_mul_f32 v[4:5], v[4:5], v[0:1] op_sel_hi:[1,0]
	v_pk_mul_f32 v[22:23], v[22:23], v[0:1] op_sel_hi:[1,0]
	v_pk_mul_f32 v[24:25], v[24:25], v[0:1] op_sel_hi:[1,0]
	v_pk_mul_f32 v[26:27], v[26:27], v[0:1] op_sel_hi:[1,0]
	v_pk_mul_f32 v[28:29], v[28:29], v[0:1] op_sel_hi:[1,0]
	v_pk_mul_f32 v[30:31], v[30:31], v[0:1] op_sel_hi:[1,0]
	v_pk_mul_f32 v[32:33], v[32:33], v[0:1] op_sel_hi:[1,0]
	s_waitcnt vmcnt(7)
	v_lshlrev_b32_e32 v40, 16, v42
	v_and_b32_e32 v41, 0xffff0000, v42
	v_lshlrev_b32_e32 v42, 16, v43
	v_and_b32_e32 v43, 0xffff0000, v43
	s_waitcnt vmcnt(3)
	v_lshlrev_b32_e32 v60, 16, v50
	v_and_b32_e32 v61, 0xffff0000, v50
	v_lshlrev_b32_e32 v50, 16, v51
	v_and_b32_e32 v51, 0xffff0000, v51
	v_lshlrev_b32_e32 v54, 16, v44
	v_and_b32_e32 v55, 0xffff0000, v44
	v_lshlrev_b32_e32 v44, 16, v45
	v_and_b32_e32 v45, 0xffff0000, v45
	v_lshlrev_b32_e32 v56, 16, v46
	v_and_b32_e32 v57, 0xffff0000, v46
	v_lshlrev_b32_e32 v46, 16, v47
	v_and_b32_e32 v47, 0xffff0000, v47
	v_lshlrev_b32_e32 v58, 16, v48
	v_and_b32_e32 v59, 0xffff0000, v48
	v_lshlrev_b32_e32 v48, 16, v49
	v_and_b32_e32 v49, 0xffff0000, v49
	v_pk_mul_f32 v[18:19], v[18:19], v[40:41]
	v_pk_mul_f32 v[20:21], v[20:21], v[42:43]
	v_pk_mul_f32 v[2:3], v[2:3], v[60:61]
	v_pk_mul_f32 v[4:5], v[4:5], v[50:51]
	v_pk_mul_f32 v[22:23], v[22:23], v[54:55]
	v_pk_mul_f32 v[24:25], v[24:25], v[44:45]
	v_pk_mul_f32 v[26:27], v[26:27], v[56:57]
	v_pk_mul_f32 v[28:29], v[28:29], v[46:47]
	v_pk_mul_f32 v[30:31], v[30:31], v[58:59]
	v_pk_mul_f32 v[32:33], v[32:33], v[48:49]
	v_cvt_pk_bf16_f32 v18, v18, v19
	v_cvt_pk_bf16_f32 v19, v20, v21
	v_cvt_pk_bf16_f32 v2, v2, v3
	v_cvt_pk_bf16_f32 v3, v4, v5
	v_cvt_pk_bf16_f32 v20, v22, v23
	v_cvt_pk_bf16_f32 v21, v24, v25
	v_cvt_pk_bf16_f32 v22, v26, v27
	v_cvt_pk_bf16_f32 v23, v28, v29
	v_cvt_pk_bf16_f32 v24, v30, v31
	v_cvt_pk_bf16_f32 v25, v32, v33
	global_store_dwordx2 v[36:37], v[18:19], off
	global_store_dwordx2 v[36:37], v[20:21], off offset:16
	global_store_dwordx2 v[36:37], v[22:23], off offset:32
	global_store_dwordx2 v[36:37], v[24:25], off offset:48
	global_store_dwordx2 v[36:37], v[2:3], off offset:64
	s_waitcnt vmcnt(7)
	v_lshlrev_b32_e32 v2, 16, v52
	v_and_b32_e32 v3, 0xffff0000, v52
	v_pk_mul_f32 v[4:5], v[6:7], v[0:1] op_sel_hi:[1,0]
	v_pk_mul_f32 v[6:7], v[8:9], v[0:1] op_sel_hi:[1,0]
	v_pk_mul_f32 v[2:3], v[4:5], v[2:3]
	v_lshlrev_b32_e32 v4, 16, v53
	v_and_b32_e32 v5, 0xffff0000, v53
	v_pk_mul_f32 v[4:5], v[6:7], v[4:5]
	v_cvt_pk_bf16_f32 v2, v2, v3
	v_cvt_pk_bf16_f32 v3, v4, v5
	global_store_dwordx2 v[36:37], v[2:3], off offset:80
	s_waitcnt vmcnt(7)
	v_lshlrev_b32_e32 v2, 16, v34
	v_and_b32_e32 v3, 0xffff0000, v34
	v_pk_mul_f32 v[4:5], v[10:11], v[0:1] op_sel_hi:[1,0]
	v_pk_mul_f32 v[6:7], v[12:13], v[0:1] op_sel_hi:[1,0]
	v_pk_mul_f32 v[2:3], v[4:5], v[2:3]
	v_lshlrev_b32_e32 v4, 16, v35
	v_and_b32_e32 v5, 0xffff0000, v35
	v_pk_mul_f32 v[4:5], v[6:7], v[4:5]
	v_cvt_pk_bf16_f32 v2, v2, v3
	v_cvt_pk_bf16_f32 v3, v4, v5
	global_store_dwordx2 v[36:37], v[2:3], off offset:96
	s_waitcnt vmcnt(7)
	v_lshlrev_b32_e32 v2, 16, v38
	v_and_b32_e32 v3, 0xffff0000, v38
	v_pk_mul_f32 v[4:5], v[14:15], v[0:1] op_sel_hi:[1,0]
	v_pk_mul_f32 v[6:7], v[16:17], v[0:1] op_sel_hi:[1,0]
	v_pk_mul_f32 v[2:3], v[4:5], v[2:3]
	v_lshlrev_b32_e32 v4, 16, v39
	v_and_b32_e32 v5, 0xffff0000, v39
	v_pk_mul_f32 v[4:5], v[6:7], v[4:5]
	v_cvt_pk_bf16_f32 v2, v2, v3
	v_cvt_pk_bf16_f32 v3, v4, v5
	global_store_dwordx2 v[36:37], v[2:3], off offset:112
	s_branch .LBB0_828
